# seam: first look at the team's flags issued right after the own flag store, in flight under the LDS reads
# baseline (speedup 1.0000x reference)
.Lxb_noinv:
	s_or_b64 exec, exec, s[4:5]
	v_cmp_eq_u32_e32 vcc, 0, v210
	s_and_saveexec_b64 s[4:5], vcc
	s_cbranch_execz .LBB0_463
	v_readlane_b32 s6, v240, 5
	v_readlane_b32 s7, v240, 6
	v_readlane_b32 s8, v240, 0
	s_add_i32 s101, s101, 1
	v_mov_b32_e32 v2, s101
	s_and_b32 s9, s8, 7
	s_lshl_b32 s9, s9, 8
	s_add_u32 s9, s9, 0x12000
	s_add_u32 s12, s6, s9
	s_addc_u32 s13, s7, 0
	s_lshr_b32 s9, s8, 3
	s_lshl_b32 s9, s9, 2
	v_mov_b32_e32 v3, s9
	global_store_dword v3, v2, s[12:13]
	s_bfe_u32 s9, s8, 0x20003
	s_lshl_b32 s9, s9, 2
	s_mov_b32 exec_lo, 0xff
	s_mov_b32 exec_hi, 0
	v_mbcnt_lo_u32_b32 v5, -1, 0
	v_lshlrev_b32_e32 v5, 4, v5
	v_add_u32_e32 v5, s9, v5
	global_load_dword v6, v5, s[12:13] sc1
	s_mov_b64 exec, 1
	v_readlane_b32 s6, v240, 60
	s_and_b32 s3, s3, 15
	s_lshl_b32 s3, s3, 8
	v_mov_b32_e32 v0, s6
	ds_read_b64 v[0:1], v0
	v_readlane_b32 s6, v240, 5
	v_readlane_b32 s7, v240, 6
	s_waitcnt lgkmcnt(0)
	v_cmp_ne_u32_e32 vcc, 0, v0
	s_cbranch_vccnz .Lxb_have
	s_mov_b32 s12, 0

.Lxb_have:
	v_readfirstlane_b32 s10, v0
	v_readfirstlane_b32 s11, v1
	v_readlane_b32 s8, v240, 60
	v_mov_b32_e32 v2, 1
	s_nop 1
	v_mov_b32_e32 v4, s8
	ds_read_b32 v4, v4 offset:8
	v_readlane_b32 s8, v240, 0
	s_nop 0
	s_lshl_b32 s9, s8, 6
	s_add_u32 s9, s9, 0x4000
	s_add_u32 s14, s6, s9
	s_addc_u32 s15, s7, 0
	s_waitcnt lgkmcnt(0)
	v_readfirstlane_b32 s9, v4
	s_cmp_eq_u32 s9, 1
	s_cbranch_scc0 .Lxb_grid
	s_mov_b32 s9, 0x3cfdf3f4
	s_bitcmp1_b32 s9, s70
	s_cbranch_scc0 .Lxb_grid
	s_and_b32 s9, s8, 7
	s_lshl_b32 s9, s9, 8
	s_add_u32 s9, s9, 0x12000
	s_add_u32 s12, s6, s9
	s_addc_u32 s13, s7, 0
	s_lshr_b32 s9, s8, 3
	s_lshl_b32 s9, s9, 2
	s_bfe_u32 s9, s8, 0x20003
	s_lshl_b32 s9, s9, 2
	s_mov_b32 exec_lo, 0xff
	s_mov_b32 exec_hi, 0
	v_mbcnt_lo_u32_b32 v3, -1, 0
	v_lshlrev_b32_e32 v3, 4, v3
	v_add_u32_e32 v3, s9, v3
	s_mov_b32 s9, 0
	s_waitcnt vmcnt(0)
	v_cmp_gt_u32_e32 vcc, s101, v6
	s_cbranch_vccz .Lxb_ldone
